# v75 + counted-wait ladders on the next-tile LDS commit merged into one wait in the five attention key loops (13 fewer s_waitcnt per key tile set) and one redundant s_nop 11 dropped
# speedup vs baseline: 1.0015x; 1.0015x over previous
; DI void phase_attn_swa(const Params& P, const float* sinks, bf16_t* og, unsigned char* smem, int L, int G) {
;     ...
;     for (int j = jlo; j <= jhi; ++j) {
;       const int key0 = j * 64, cb = (j - jlo) & 1;
;       __syncthreads();
;       if (j < jhi) kv64_store(R, sK + (cb ^ 1) * KVB64, sVt + (cb ^ 1) * KVB64, tid);
;       if (j + 1 < jhi) kv64_fetch(R, kb, 256, vb, SEQ, key0 + 128, true, tid);
.LBB0_346:
	s_add_i32 s1, s46, s47
	s_and_b32 s0, s47, 1
	s_cmp_ge_u32 s1, s41
	s_waitcnt lgkmcnt(0)
	s_barrier
	s_cbranch_scc1 .LBB0_348
	s_xor_b32 s48, s0, 1
	s_mulk_i32 s48, 0x4800
	v_add_u32_e32 v32, s48, v160
	s_waitcnt vmcnt(0)
	ds_write_b128 v32, v[80:83]
	ds_write_b128 v32, v[84:87] offset:4608
	ds_write_b128 v32, v[88:91] offset:9216
	ds_write_b128 v32, v[92:95] offset:13824

; DI void kv96x8_store(const KVR8& R, bf16_t* sK, bf16_t* sVt, int tid) {
;   const int row = tid >> 3, kc = tid & 7, rr = (tid & 255) >> 2, rc = tid & 3;
;   *(u32x4*)(sK + row * 104 + kc * 8) = R.k0;
;   if (tid < 256) *(u32x4*)(sK + rr * 104 + 64 + rc * 8) = R.k2;
;   *(u32x4*)(sVt + row * 72 + kc * 8) = R.v0;
; }
; DI void phase_attn_mla(const Params& P, bf16_t* og, unsigned char* smem, int L, int G) {
;     ...
;       __syncthreads();
;       if (j < jhi) kv96x8_store(R, sK + (cb ^ 1) * KVB96, sVt + (cb ^ 1) * KVB96, tid);
;       if (j + 1 < jhi) kv96x8_fetch(R, knb, krb, vb, key0 + 128, tid);
.Lmy_mla_go:
	s_cmp_ge_u32 s26, s19
	s_cbranch_scc1 .LBB0_783
	s_xor_b32 s24, s40, 1
	s_mulk_i32 s24, 0x2c00
	s_lshl_b32 s25, s24, 1
	v_add3_u32 v0, s25, v180, v158
	s_waitcnt vmcnt(0)
	ds_write_b128 v0, v[108:111]
	s_and_saveexec_b64 s[22:23], s[12:13]
	v_add3_u32 v0, s25, v151, v160
	ds_write_b128 v0, v[104:107] offset:128
	s_or_b64 exec, exec, s[22:23]
	v_lshl_add_u32 v0, s24, 1, v142
	ds_write_b128 v0, v[112:115] offset:13312
	s_mov_b64 s[100:101], exec
	s_mov_b64 exec, 1
	ds_write_b32 v252, v254 offset:32
	s_mov_b64 exec, s[100:101]

; DI void phase_attn_nsa(const Params& P, bf16_t* og, unsigned char* smem, int L, int G) {
;     ...
;       for (int j = 0; j <= jhi; ++j) {
;         const int key0 = j * 64, cb = j & 1;
;         __syncthreads();
;         if (j < jhi) kv64_store(R, sK + (cb ^ 1) * KVB64, sVt + (cb ^ 1) * KVB64, tid);
;         if (j + 1 < jhi) kv64_fetch(R, kb, 256, vb, SEQ, key0 + 128, true, tid);
.LBB0_1345:
	s_and_b32 s5, s0, 1
	s_cmp_ge_u32 s0, s20
	s_waitcnt lgkmcnt(0)
	s_barrier
	s_cbranch_scc1 .LBB0_1347
	s_xor_b32 s1, s5, 1
	s_mulk_i32 s1, 0x4800
	v_add_u32_e32 v0, s1, v170
	s_waitcnt vmcnt(0)
	ds_write_b128 v0, v[90:93]
	ds_write_b128 v0, v[94:97] offset:4608
	ds_write_b128 v0, v[98:101] offset:9216
	ds_write_b128 v0, v[102:105] offset:13824

; #define MFMA(a, b, c) __builtin_amdgcn_mfma_f32_32x32x16_bf16((a), (b), (c), 0, 0, 0)
; DI float shx(float v, int m) { return __shfl_xor(v, m, 64); }
; template <int DQK, bool MASKED, int MODE, class MF>
; DI void attn_step(const bf16_t* sK, const bf16_t* sVt, const bf16x8 (&qf)[DQK / 16], f32x16& o0, f32x16& o1, float& m, float& l,
;                   float sc, const MF& mf, int lane, f32x16 (&s)[2], float invl, bool lanevalid = true) {
;     ...
;   bf16x8 kf[2][DQK / 16];
; #pragma unroll
;   for (int sub = 0; sub < 2; ++sub)
; #pragma unroll
;     for (int ks = 0; ks < DQK / 16; ++ks) kf[sub][ks] = *(const bf16x8*)(sK + (sub * 32 + pr) * KST + ks * 16 + 8 * h);
;   __builtin_amdgcn_sched_barrier(0);
; #pragma unroll
;   for (int q = 0; q < 16; ++q) { s[0][q] = 0.f; s[1][q] = 0.f; }
; #pragma unroll
;   for (int ks = 0; ks < DQK / 16; ++ks) {
;     s[0] = MFMA(kf[0][ks], qf[ks], s[0]);
;     s[1] = MFMA(kf[1][ks], qf[ks], s[1]);
;   }
;   bf16x8 vf[2][2][2];
;   if (MODE != 1) {
; #pragma unroll
;     for (int sub = 0; sub < 2; ++sub)
; #pragma unroll
;       for (int s2 = 0; s2 < 2; ++s2) {
;         vf[sub][s2][0] = *(const bf16x8*)(sVt + r * 72 + sub * 32 + s2 * 16 + 8 * h);
;         vf[sub][s2][1] = *(const bf16x8*)(sVt + (32 + r) * 72 + sub * 32 + s2 * 16 + 8 * h);
;       }
;     __builtin_amdgcn_sched_barrier(0);
;   }
;   float mxr = -3.0e38f;
; #pragma unroll
;   for (int sub = 0; sub < 2; ++sub)
; #pragma unroll
;     for (int q = 0; q < 16; ++q) {
;       if (MASKED) { const int kk = sub * 32 + 16 * (q >> 3) + 8 * h + (q & 7); s[sub][q] = mf(kk) ? s[sub][q] : -3.0e38f; }
;       if (MODE != 2) mxr = fmaxf(mxr, s[sub][q]);
;     }
;   float alpha = 1.f;
;   if (MODE != 2) {
;     float mx = fmaxf(m, mxr * sc);
;     mx = fmaxf(mx, shx(mx, 32));
; DI void phase_attn_nsa(const Params& P, bf16_t* og, unsigned char* smem, int L, int G) {
;     ...
;         if ((selU >> j) & 1u) {
;           const bool lsel = (sel >> j) & 1u;
;           auto mf = [&](int kk) { return lsel && (key0 + kk <= t); };
;           if (key0 + 63 > t0) attn_step<64, true, 0>(sK + cb * KVB64, sVt + cb * KVB64, qf, o0, o1, m, l, sc, mf, lane, s, 0.f);
;           else attn_step<64, false, 0>(sK + cb * KVB64, sVt + cb * KVB64, qf, o0, o1, m, l, sc, mf, lane, s, 0.f, lsel);
.LBB0_1349:
	s_lshr_b32 s1, s2, s0
	s_bitcmp0_b32 s1, 0
	s_cbranch_scc1 .LBB0_1355
	v_lshrrev_b32_e32 v0, s0, v183
	s_add_i32 s6, s44, 63
	s_mulk_i32 s5, 0x4800
	v_and_b32_e32 v190, 1, v0
	s_mov_b64 s[0:1], -1
	s_cmp_le_u32 s6, s46
	v_max_f32_e32 v188, v141, v141
	v_add_u32_e32 v189, s5, v153
	v_cmp_eq_u32_e32 vcc, 1, v190
	s_cbranch_scc0 .LBB0_1352
	v_add_u32_e32 v0, s5, v182
	ds_read_b128 v[34:37], v0
	ds_read_b128 v[38:41], v0 offset:32
	ds_read_b128 v[106:109], v0 offset:64
	ds_read_b128 v[110:113], v0 offset:96
	ds_read_b128 v[42:45], v0 offset:4608
	ds_read_b128 v[114:117], v0 offset:4640
	ds_read_b128 v[118:121], v0 offset:4672
	ds_read_b128 v[194:197], v0 offset:4704
	s_waitcnt lgkmcnt(7)
	v_mfma_f32_32x32x16_bf16 v[58:73], v[34:37], v[74:77], 0
	v_add3_u32 v0, v189, v175, v138
	v_add3_u32 v34, v189, v177, v138
	s_waitcnt lgkmcnt(3)
	v_mfma_f32_32x32x16_bf16 v[42:57], v[42:45], v[74:77], 0
	v_mfma_f32_32x32x16_bf16 v[58:73], v[38:41], v[78:81], v[58:73]
	s_waitcnt lgkmcnt(2)
	v_mfma_f32_32x32x16_bf16 v[42:57], v[114:117], v[78:81], v[42:57]
	v_mfma_f32_32x32x16_bf16 v[58:73], v[106:109], v[82:85], v[58:73]
	s_waitcnt lgkmcnt(1)
	v_mfma_f32_32x32x16_bf16 v[42:57], v[118:121], v[82:85], v[42:57]
	v_mfma_f32_32x32x16_bf16 v[58:73], v[110:113], v[86:89], v[58:73]
	ds_read_b128 v[198:201], v0 offset:9216
	ds_read_b128 v[126:129], v0 offset:9248
	ds_read_b128 v[130:133], v34 offset:9216
	ds_read_b128 v[122:125], v34 offset:9248
	ds_read_b128 v[118:121], v0 offset:9280
	ds_read_b128 v[110:113], v0 offset:9312
	ds_read_b128 v[114:117], v34 offset:9280
	ds_read_b128 v[106:109], v34 offset:9312
	s_waitcnt lgkmcnt(8)
	v_mfma_f32_32x32x16_bf16 v[42:57], v[194:197], v[86:89], v[42:57]
	s_nop 1
	v_max3_f32 v0, v58, s8, v59
	v_max3_f32 v0, v0, v60, v61
	v_max3_f32 v0, v0, v62, v63
	v_max3_f32 v0, v0, v64, v65
	v_max3_f32 v0, v0, v66, v67
	v_max3_f32 v0, v0, v68, v69
	v_max3_f32 v0, v0, v70, v71
	v_max3_f32 v0, v0, v72, v73
	s_nop 1
	v_max3_f32 v0, v0, v42, v43
	v_max3_f32 v0, v0, v44, v45
	v_max3_f32 v0, v0, v46, v47
	v_max3_f32 v0, v0, v48, v49
	v_max3_f32 v0, v0, v50, v51
	v_max3_f32 v0, v0, v52, v53
	v_max3_f32 v0, v0, v54, v55
	v_max3_f32 v0, v0, v56, v57
	v_mul_f32_e32 v0, 0x3e38aa3b, v0
	v_max_f32_e32 v0, v188, v0
	ds_bpermute_b32 v34, v173, v0
	s_mov_b64 s[0:1], 0
	s_waitcnt lgkmcnt(0)
; #define MFMA(a, b, c) __builtin_amdgcn_mfma_f32_32x32x16_bf16((a), (b), (c), 0, 0, 0)
; DI unsigned pack2(float a, float b) { f32x2_t v = {a, b}; bf16x2_t r = __builtin_convertvector(v, bf16x2_t); return __builtin_bit_cast(unsigned, r); }
; DI float fexp2(float x) { return __builtin_amdgcn_exp2f(x); }
; DI float shx(float v, int m) { return __shfl_xor(v, m, 64); }
; template <int DQK, bool MASKED, int MODE, class MF>
; DI void attn_step(const bf16_t* sK, const bf16_t* sVt, const bf16x8 (&qf)[DQK / 16], f32x16& o0, f32x16& o1, float& m, float& l,
;                   float sc, const MF& mf, int lane, f32x16 (&s)[2], float invl, bool lanevalid = true) {
;     ...
;   float alpha = 1.f;
;   if (MODE != 2) {
;     float mx = fmaxf(m, mxr * sc);
;     mx = fmaxf(mx, shx(mx, 32));
;     if (!MASKED) mx = lanevalid ? mx : m;
;     alpha = fexp2(m - mx);
;     m = mx;
;   }
;   const float moff = (!MASKED && !lanevalid) ? 1.0e30f : m;
;   float ps = 0.f;
; #pragma unroll
;   for (int sub = 0; sub < 2; ++sub)
; #pragma unroll
;     for (int q = 0; q < 16; ++q) {
;       float pv = fexp2(__builtin_fmaf(s[sub][q], sc, -moff));
;       if (MASKED && MODE != 0) pv = (s[sub][q] > -1.0e38f) ? pv : 0.f;
;       if (MODE == 2) pv *= invl;
;       s[sub][q] = pv;
;       ps += pv;
;     }
;   if (MODE != 2) {
;     ps += shx(ps, 32);
;     l = l * alpha + ps;
;   }
;   if (MODE == 1) return;
;   if (MODE == 0) {
; #pragma unroll
;     for (int q = 0; q < 16; ++q) { o0[q] *= alpha; o1[q] *= alpha; }
;   }
; #pragma unroll
;   for (int sub = 0; sub < 2; ++sub)
; #pragma unroll
;     for (int s2 = 0; s2 < 2; ++s2) {
;       union { bf16x8 v; unsigned u[4]; } pb;
; #pragma unroll
;       for (int e = 0; e < 4; ++e) pb.u[e] = pack2(s[sub][8 * s2 + 2 * e], s[sub][8 * s2 + 2 * e + 1]);
;       o0 = MFMA(vf[sub][s2][0], pb.v, o0);
;       o1 = MFMA(vf[sub][s2][1], pb.v, o1);
;     }
	v_max_f32_e32 v34, v34, v34
	v_max_f32_e32 v34, v0, v34
	v_cndmask_b32_e64 v191, v167, -v34, vcc
	v_fmamk_f32 v35, v58, 0x3e38aa3b, v191
	v_fmamk_f32 v36, v59, 0x3e38aa3b, v191
	v_exp_f32_e32 v58, v35
	v_fmamk_f32 v37, v60, 0x3e38aa3b, v191
	v_exp_f32_e32 v59, v36
	v_exp_f32_e32 v60, v37
	v_fmamk_f32 v35, v61, 0x3e38aa3b, v191
	v_exp_f32_e32 v61, v35
	v_add_f32_e32 v36, 0, v58
	v_fmamk_f32 v35, v62, 0x3e38aa3b, v191
	v_add_f32_e32 v36, v59, v36
	v_exp_f32_e32 v62, v35
	v_fmamk_f32 v35, v63, 0x3e38aa3b, v191
	v_add_f32_e32 v36, v60, v36
	v_exp_f32_e32 v63, v35
	v_fmamk_f32 v35, v64, 0x3e38aa3b, v191
	v_exp_f32_e32 v64, v35
	v_add_f32_e32 v35, v61, v36
	v_fmamk_f32 v36, v65, 0x3e38aa3b, v191
	v_exp_f32_e32 v65, v36
	v_fmamk_f32 v36, v66, 0x3e38aa3b, v191
	v_add_f32_e32 v35, v62, v35
	v_exp_f32_e32 v203, v36
	v_fmamk_f32 v36, v67, 0x3e38aa3b, v191
	v_add_f32_e32 v35, v63, v35
	v_exp_f32_e32 v204, v36
	v_fmamk_f32 v36, v68, 0x3e38aa3b, v191
	v_add_f32_e32 v35, v64, v35
	v_exp_f32_e32 v205, v36
	v_fmamk_f32 v36, v69, 0x3e38aa3b, v191
	v_add_f32_e32 v35, v65, v35
	v_exp_f32_e32 v206, v36
	v_fmamk_f32 v36, v70, 0x3e38aa3b, v191
	v_add_f32_e32 v35, v203, v35
	v_exp_f32_e32 v207, v36
	v_fmamk_f32 v36, v71, 0x3e38aa3b, v191
	v_add_f32_e32 v35, v204, v35
	v_exp_f32_e32 v208, v36
	v_fmamk_f32 v36, v72, 0x3e38aa3b, v191
	v_add_f32_e32 v35, v205, v35
	v_exp_f32_e32 v209, v36
	v_fmamk_f32 v36, v73, 0x3e38aa3b, v191
	v_add_f32_e32 v35, v206, v35
	v_exp_f32_e32 v210, v36
	v_fmamk_f32 v36, v42, 0x3e38aa3b, v191
	v_add_f32_e32 v35, v207, v35
	v_exp_f32_e32 v211, v36
	v_fmamk_f32 v36, v43, 0x3e38aa3b, v191
	v_add_f32_e32 v35, v208, v35
	v_exp_f32_e32 v212, v36
	v_fmamk_f32 v36, v44, 0x3e38aa3b, v191
	v_add_f32_e32 v35, v209, v35
	v_exp_f32_e32 v213, v36
	v_fmamk_f32 v36, v45, 0x3e38aa3b, v191
	v_add_f32_e32 v35, v210, v35
	v_exp_f32_e32 v214, v36
	v_fmamk_f32 v36, v46, 0x3e38aa3b, v191
	v_add_f32_e32 v35, v211, v35
	v_exp_f32_e32 v215, v36
	v_fmamk_f32 v36, v47, 0x3e38aa3b, v191
	v_cndmask_b32_e32 v0, v141, v34, vcc
	v_add_f32_e32 v35, v212, v35
	v_exp_f32_e32 v216, v36
	v_fmamk_f32 v36, v48, 0x3e38aa3b, v191
	v_sub_f32_e32 v34, v141, v0
	v_add_f32_e32 v35, v213, v35
	v_exp_f32_e32 v217, v36
	v_add_f32_e32 v35, v214, v35
	v_exp_f32_e32 v202, v34
	v_add_f32_e32 v35, v215, v35
	v_add_f32_e32 v35, v216, v35
	v_add_f32_e32 v218, v217, v35
	v_fmamk_f32 v35, v49, 0x3e38aa3b, v191
	v_fmamk_f32 v34, v50, 0x3e38aa3b, v191
	v_exp_f32_e32 v219, v35
	v_exp_f32_e32 v220, v34
	v_pk_mul_f32 v[32:33], v[32:33], v[202:203] op_sel_hi:[1,0]
	v_pk_mul_f32 v[30:31], v[30:31], v[202:203] op_sel_hi:[1,0]
	v_pk_mul_f32 v[28:29], v[28:29], v[202:203] op_sel_hi:[1,0]
	v_pk_mul_f32 v[26:27], v[26:27], v[202:203] op_sel_hi:[1,0]
	v_pk_mul_f32 v[24:25], v[24:25], v[202:203] op_sel_hi:[1,0]
	v_pk_mul_f32 v[22:23], v[22:23], v[202:203] op_sel_hi:[1,0]
	v_pk_mul_f32 v[20:21], v[20:21], v[202:203] op_sel_hi:[1,0]
	v_pk_mul_f32 v[18:19], v[18:19], v[202:203] op_sel_hi:[1,0]
	v_cvt_pk_bf16_f32 v194, v58, v59
	v_cvt_pk_bf16_f32 v195, v60, v61
	v_cvt_pk_bf16_f32 v196, v62, v63
	v_cvt_pk_bf16_f32 v197, v64, v65
	v_pk_mul_f32 v[16:17], v[16:17], v[202:203] op_sel_hi:[1,0]
	v_pk_mul_f32 v[14:15], v[14:15], v[202:203] op_sel_hi:[1,0]
	v_mfma_f32_32x32x16_bf16 v[18:33], v[198:201], v[194:197], v[18:33]
	v_mul_f32_e64 v12, v12, v202
	v_mul_f32_e64 v13, v13, v202
	v_mul_f32_e64 v10, v10, v202
	v_mul_f32_e64 v11, v11, v202
	v_mul_f32_e64 v8, v8, v202
	v_mul_f32_e64 v9, v9, v202
	v_pk_mul_f32 v[6:7], v[6:7], v[202:203] op_sel_hi:[1,0]
	v_pk_mul_f32 v[4:5], v[4:5], v[202:203] op_sel_hi:[1,0]
	v_pk_mul_f32 v[2:3], v[2:3], v[202:203] op_sel_hi:[1,0]
	v_fmamk_f32 v51, v51, 0x3e38aa3b, v191
	v_add_f32_e32 v50, v219, v218
	v_mfma_f32_32x32x16_bf16 v[2:17], v[130:133], v[194:197], v[2:17]
	v_cvt_pk_bf16_f32 v130, v203, v204
	v_cvt_pk_bf16_f32 v131, v205, v206
	v_cvt_pk_bf16_f32 v132, v207, v208
	v_cvt_pk_bf16_f32 v133, v209, v210
	v_add_f32_e32 v50, v220, v50
	v_fmamk_f32 v55, v55, 0x3e38aa3b, v191
	v_exp_f32_e32 v55, v55
	v_mfma_f32_32x32x16_bf16 v[18:33], v[126:129], v[130:133], v[18:33]
	v_exp_f32_e32 v126, v51
	v_fmamk_f32 v51, v52, 0x3e38aa3b, v191
	v_exp_f32_e32 v127, v51
	v_fmamk_f32 v51, v53, 0x3e38aa3b, v191
	v_exp_f32_e32 v128, v51
	v_add_f32_e32 v50, v126, v50
	v_add_f32_e32 v50, v127, v50
	v_mfma_f32_32x32x16_bf16 v[2:17], v[122:125], v[130:133], v[2:17]
	v_add_f32_e32 v122, v128, v50
	v_fmamk_f32 v50, v54, 0x3e38aa3b, v191
	v_exp_f32_e32 v54, v50
	v_fmamk_f32 v56, v56, 0x3e38aa3b, v191
	v_exp_f32_e32 v56, v56
	v_fmac_f32_e32 v191, 0x3e38aa3b, v57
	v_cvt_pk_bf16_f32 v50, v211, v212
	v_cvt_pk_bf16_f32 v51, v213, v214
	v_cvt_pk_bf16_f32 v52, v215, v216
	v_cvt_pk_bf16_f32 v53, v217, v219
	v_exp_f32_e32 v57, v191
	s_nop 0
	v_mfma_f32_32x32x16_bf16 v[18:33], v[118:121], v[50:53], v[18:33]
	v_add_f32_e32 v118, v54, v122
	v_cvt_pk_bf16_f32 v54, v54, v55
	v_mfma_f32_32x32x16_bf16 v[2:17], v[114:117], v[50:53], v[2:17]
	v_add_f32_e32 v50, v55, v118
	v_add_f32_e32 v50, v56, v50
	v_add_f32_e32 v50, v57, v50
	v_cvt_pk_bf16_f32 v52, v220, v126
	v_cvt_pk_bf16_f32 v53, v127, v128
	v_cvt_pk_bf16_f32 v55, v56, v57
	s_nop 1
	v_mfma_f32_32x32x16_bf16 v[18:33], v[110:113], v[52:55], v[18:33]
	v_mfma_f32_32x32x16_bf16 v[2:17], v[106:109], v[52:55], v[2:17]
	v_fma_f32 v50, v185, v202, v50
	v_mov_b32_e32 v141, v0
	v_mov_b32_e32 v185, v50
	s_branch .LBB0_1355

; DI void phase_attn_nsa(const Params& P, bf16_t* og, unsigned char* smem, int L, int G) {
;     ...
;       for (int j = jlo; j <= jhi; ++j) {
;         const int key0 = j * 64, cb = (j - jlo) & 1;
;         __syncthreads();
;         if (j < jhi) kv64_store(R, sK + (cb ^ 1) * KVB64, sVt + (cb ^ 1) * KVB64, tid);
;         if (j + 1 < jhi) kv64_fetch(R, kb, 256, vb, SEQ, key0 + 128, true, tid);
.LBB0_1361:
	s_add_i32 s0, s2, s4
	s_and_b32 s5, s4, 1
	s_cmp_ge_u32 s0, s20
	s_waitcnt lgkmcnt(0)
	s_barrier
	s_cbranch_scc1 .LBB0_1363
	s_xor_b32 s1, s5, 1
	s_mulk_i32 s1, 0x4800
	v_add_u32_e32 v0, s1, v170
	s_waitcnt vmcnt(0)
	ds_write_b128 v0, v[42:45]
	ds_write_b128 v0, v[46:49] offset:4608
	ds_write_b128 v0, v[50:53] offset:9216
	ds_write_b128 v0, v[54:57] offset:13824

; DI void phase_attn_swa(const Params& P, const float* sinks, bf16_t* og, unsigned char* smem, int L, int G) {
;     ...
;     for (int j = jlo; j <= jhi; ++j) {
;       const int key0 = j * 64, cb = (j - jlo) & 1;
;       __syncthreads();
;       if (j < jhi) kv64_store(R, sK + (cb ^ 1) * KVB64, sVt + (cb ^ 1) * KVB64, tid);
;       if (j + 1 < jhi) kv64_fetch(R, kb, 256, vb, SEQ, key0 + 128, true, tid);
.LBB0_1668:
	s_add_i32 s1, s17, s18
	s_and_b32 s0, s18, 1
	s_cmp_ge_u32 s1, s11
	s_waitcnt lgkmcnt(0)
	s_barrier
	s_cbranch_scc1 .LBB0_1670
	s_xor_b32 s19, s0, 1
	s_mulk_i32 s19, 0x4800
	v_add_u32_e32 v32, s19, v160
	s_waitcnt vmcnt(0)
	ds_write_b128 v32, v[80:83]
	ds_write_b128 v32, v[84:87] offset:4608
	ds_write_b128 v32, v[88:91] offset:9216
	ds_write_b128 v32, v[92:95] offset:13824
